# baseline (speedup 1.0000x reference)
; #define PG8_STAGE(bufoff, gbase, voff) do { _Pragma("unroll") for (int _i = 0; _i < 2; ++_i) \
;         __builtin_amdgcn_global_load_lds((const unsigned*)((const char*)(gbase) + (voff)[_i]), (PG8_LAS unsigned*)(lds + (bufoff) + ldsw + _i * 8192), 16, 0, 0); } while (0)
; #define PG8_LDA(dst, b, h) do { _Pragma("unroll") for (int m = 0; m < 4; ++m) _Pragma("unroll") for (int k = 0; k < 2; ++k) dst[m][k] = *(const PG8_LAS bf16x8*)(lds + PG8_SA(b, h) + aoff + m * 2048 + k * 1024); } while (0)
; #define PG8_LDB(dst, b, h) do { _Pragma("unroll") for (int n = 0; n < 2; ++n) _Pragma("unroll") for (int k = 0; k < 2; ++k) dst[n][k] = *(const PG8_LAS bf16x8*)(lds + PG8_SB(b, h) + boff + n * 2048 + k * 1024); } while (0)
; #define PG8_WAIT_V(n) asm volatile("s_waitcnt vmcnt(" #n ")" ::: "memory")
; #define PG8_BAR __builtin_amdgcn_s_barrier()
;     __device__ __forceinline__ void operator()(const f32x4 (&acc)[2][2][4][2], const Unit& u, int wr, int wc, int fr, int fq, int) const {
;     ...
;             const f32x4 w0 = *(const f32x4*)(convw + c0), w1 = *(const f32x4*)(convw + 1024 + c0), w2 = *(const f32x4*)(convw + 2048 + c0), ga = *(const f32x4*)(gconv + c0);
;             float rsv[2][4];
; #pragma unroll
;             for (int ai = 0; ai < 2; ++ai)
; #pragma unroll
;                 for (int m = 0; m < 4; ++m) rsv[ai][m] = __builtin_amdgcn_rsqf(rowss[row0 + ai * HALF + m * 16] * (1.0f / 1024.0f) + RMS_EPS);
; template <class Epi, class Sched, bool ALIGN_EPI = false, bool SP2 = false>
; __device__ __forceinline__ void gemm_phase(PG8_LAS unsigned char* lds, const Gemm g, const Sched& S, const Epi& E) {
;     ...
;             if constexpr (Epi::MIDSCALE) { if (t == (nt >> 1)) E.midscale(acc, cur, wr, fr, ui); }
;             const bool last = (t == nt - 2);
;             const char* a1 = cA + (size_t)(t >> 1) * apair + kstep;
;             const char* a2 = last ? nA : cA + (size_t)((t >> 1) + 1) * apair; const char* b2 = last ? nB : cB + (size_t)(t + 2) * kstep;
;             const char* a3 = a2 + kstep; const char* b3 = b2 + kstep;
;             if (last && has_next) S.a_ready(nxt, ui + 1);
;             if constexpr (SP2) {
;             PG8_LDB(B0, 0, 0); PG8_LDB(B1, 0, 1); PG8_SCHED; PG8_LDA(At, 0, 0); PG8_STAGE(PG8_SA(1, 1), a1 + hstepA, voffA);
;             PG8_WAIT_V(8); PG8_WAIT_L(0); PG8_BAR; PG8_MMA(0, 0, At, B0); PG8_MMA(0, 1, At, B1); PG8_BAR; PG8_SCHED;
.LBB0_245:
	s_ashr_i32 s63, s62, 31
	s_lshl_b64 s[26:27], s[62:63], 19
	s_add_u32 s52, s80, s26
	s_addc_u32 s53, s81, s27
	s_and_b64 s[26:27], s[8:9], exec
	s_cselect_b32 s21, s53, s11
	s_cselect_b32 s28, s52, s10
	s_ashr_i32 s43, s42, 31
	s_lshl_b64 s[26:27], s[42:43], 19
	s_add_u32 s26, s82, s26
	s_addc_u32 s27, s83, s27
	s_and_b64 s[44:45], s[8:9], exec
	s_cselect_b32 s43, s27, s13
	s_cselect_b32 s46, s26, s12
	s_add_u32 s10, s10, 0x40080
	s_addc_u32 s11, s11, 0
	s_add_u32 s47, s12, 0x100
	v_mov_b32_e32 v2, 0
	s_addc_u32 s63, s13, 0
	s_mov_b32 vcc_lo, -2
	s_waitcnt lgkmcnt(0)
	s_cmp_gt_i32 s20, 15
	s_cbranch_scc1 .Lpf_skip
	s_lshl_b32 s100, s50, 8
	s_add_i32 s101, s100, s0
	s_cmp_gt_i32 s101, 0xffff
	s_cbranch_scc1 .Lpf_skip
	s_lshr_b32 s101, s17, 10
	v_mov_b32_e32 v231, 0
	s_cmp_gt_u32 s101, 3
	s_cbranch_scc1 .Lpf_w
	s_lshl_b32 s101, s101, 6
	s_add_i32 s100, s100, s101
	v_add_u32_e32 v230, s100, v174
	v_lshl_add_u64 v[230:231], v[230:231], 2, s[68:69]
	s_branch .Lpf_go
.Lpf_w:
	s_lshl_b32 s100, s20, 6
	v_add_u32_e32 v230, s100, v174
	s_cmp_eq_u32 s101, 4
	s_cbranch_scc1 .Lpf_a0
	s_cmp_eq_u32 s101, 5
	s_cbranch_scc1 .Lpf_a1
	s_cmp_eq_u32 s101, 6
	s_cbranch_scc1 .Lpf_a2
	v_lshl_add_u64 v[230:231], v[230:231], 2, s[74:75]
	s_branch .Lpf_go
.Lpf_a0:
	v_lshl_add_u64 v[230:231], v[230:231], 2, s[72:73]
	s_branch .Lpf_go
.Lpf_a1:
	v_lshl_add_u64 v[230:231], v[230:231], 2, s[96:97]
	s_branch .Lpf_go
.Lpf_a2:
	v_lshl_add_u64 v[230:231], v[230:231], 2, s[98:99]
.Lpf_go:
	s_lshr_b32 s100, s17, 2
	s_add_i32 m0, s100, 0x21000
	s_nop 0
	global_load_lds_dword v[230:231], off
.Lpf_skip:
	s_add_u32 s12, s10, 0xfffc0080
	s_addc_u32 s13, s11, -1
	s_add_i32 s94, 0, 0x10000
	s_cmp_eq_u32 vcc_lo, 12
	s_cselect_b32 s45, s21, s13
	s_cselect_b32 s44, s28, s12
	v_add_u32_e32 v0, s94, v179
	s_cselect_b32 s13, s43, s63
	s_cselect_b32 s12, s46, s47
	s_add_i32 vcc_hi, 0, 0x14000
	ds_read_b128 v[130:133], v0
	ds_read_b128 v[134:137], v0 offset:1024
	ds_read_b128 v[138:141], v0 offset:2048
	ds_read_b128 v[142:145], v0 offset:3072
	v_add_u32_e32 v0, vcc_hi, v179
	ds_read_b128 v[146:149], v0
	ds_read_b128 v[170:173], v0 offset:1024
	ds_read_b128 v[190:193], v0 offset:2048
	ds_read_b128 v[194:197], v0 offset:3072
	v_lshl_add_u64 v[150:151], s[10:11], 0, v[162:163]
	s_add_i32 m0, s17, 0xc000
	ds_read_b128 v[198:201], v186
	ds_read_b128 v[202:205], v186 offset:1024
	ds_read_b128 v[206:209], v186 offset:2048
	ds_read_b128 v[210:213], v186 offset:3072
	ds_read_b128 v[214:217], v186 offset:4096
	ds_read_b128 v[218:221], v186 offset:5120
	ds_read_b128 v[222:225], v186 offset:6144
	ds_read_b128 v[226:229], v186 offset:7168
	global_load_lds_dwordx4 v[150:151], off
	v_lshl_add_u64 v[150:151], s[10:11], 0, v[164:165]
	s_add_i32 m0, s17, 0xe000
	s_nop 0
	global_load_lds_dwordx4 v[150:151], off
	s_waitcnt vmcnt(8)
	s_waitcnt lgkmcnt(0)
	s_barrier
	s_setprio 1
	s_waitcnt lgkmcnt(0)
	v_mfma_f32_16x16x32_bf16 v[126:129], v[130:133], v[198:201], 0
	v_mfma_f32_16x16x32_bf16 v[122:125], v[138:141], v[198:201], 0
	v_mfma_f32_16x16x32_bf16 v[110:113], v[130:133], v[206:209], 0
	v_mfma_f32_16x16x32_bf16 v[106:109], v[138:141], v[206:209], 0
	v_mfma_f32_16x16x32_bf16 v[94:97], v[130:133], v[214:217], 0
	v_mfma_f32_16x16x32_bf16 v[90:93], v[138:141], v[214:217], 0
	v_mfma_f32_16x16x32_bf16 v[78:81], v[130:133], v[222:225], 0
	v_mfma_f32_16x16x32_bf16 v[74:77], v[138:141], v[222:225], 0
	v_mfma_f32_16x16x32_bf16 v[126:129], v[134:137], v[202:205], v[126:129]
	v_mfma_f32_16x16x32_bf16 v[122:125], v[142:145], v[202:205], v[122:125]
	v_mfma_f32_16x16x32_bf16 v[110:113], v[134:137], v[210:213], v[110:113]
	v_mfma_f32_16x16x32_bf16 v[106:109], v[142:145], v[210:213], v[106:109]
	v_mfma_f32_16x16x32_bf16 v[94:97], v[134:137], v[218:221], v[94:97]
	v_mfma_f32_16x16x32_bf16 v[90:93], v[142:145], v[218:221], v[90:93]
	v_mfma_f32_16x16x32_bf16 v[78:81], v[134:137], v[226:229], v[78:81]
	v_mfma_f32_16x16x32_bf16 v[74:77], v[142:145], v[226:229], v[74:77]
	s_setprio 0
	s_setprio 1
	v_mfma_f32_16x16x32_bf16 v[118:121], v[146:149], v[198:201], 0
	v_mfma_f32_16x16x32_bf16 v[114:117], v[190:193], v[198:201], 0
	v_mfma_f32_16x16x32_bf16 v[102:105], v[146:149], v[206:209], 0
	v_mfma_f32_16x16x32_bf16 v[98:101], v[190:193], v[206:209], 0
	v_mfma_f32_16x16x32_bf16 v[86:89], v[146:149], v[214:217], 0
	v_mfma_f32_16x16x32_bf16 v[82:85], v[190:193], v[214:217], 0
	v_mfma_f32_16x16x32_bf16 v[70:73], v[146:149], v[222:225], 0
	v_mfma_f32_16x16x32_bf16 v[66:69], v[190:193], v[222:225], 0
	v_mfma_f32_16x16x32_bf16 v[118:121], v[170:173], v[202:205], v[118:121]
	v_mfma_f32_16x16x32_bf16 v[114:117], v[194:197], v[202:205], v[114:117]
	v_mfma_f32_16x16x32_bf16 v[102:105], v[170:173], v[210:213], v[102:105]
	v_mfma_f32_16x16x32_bf16 v[98:101], v[194:197], v[210:213], v[98:101]
	v_mfma_f32_16x16x32_bf16 v[86:89], v[170:173], v[218:221], v[86:89]
	v_mfma_f32_16x16x32_bf16 v[82:85], v[194:197], v[218:221], v[82:85]
	v_mfma_f32_16x16x32_bf16 v[70:73], v[170:173], v[226:229], v[70:73]
	v_mfma_f32_16x16x32_bf16 v[66:69], v[194:197], v[226:229], v[66:69]
	s_setprio 0
	s_barrier
; #define PG8_STAGE(bufoff, gbase, voff) do { _Pragma("unroll") for (int _i = 0; _i < 2; ++_i) \
;         __builtin_amdgcn_global_load_lds((const unsigned*)((const char*)(gbase) + (voff)[_i]), (PG8_LAS unsigned*)(lds + (bufoff) + ldsw + _i * 8192), 16, 0, 0); } while (0)
; #define PG8_LDA(dst, b, h) do { _Pragma("unroll") for (int m = 0; m < 4; ++m) _Pragma("unroll") for (int k = 0; k < 2; ++k) dst[m][k] = *(const PG8_LAS bf16x8*)(lds + PG8_SA(b, h) + aoff + m * 2048 + k * 1024); } while (0)
; #define PG8_LDB(dst, b, h) do { _Pragma("unroll") for (int n = 0; n < 2; ++n) _Pragma("unroll") for (int k = 0; k < 2; ++k) dst[n][k] = *(const PG8_LAS bf16x8*)(lds + PG8_SB(b, h) + boff + n * 2048 + k * 1024); } while (0)
; #define PG8_MMA(ai, bj, At, Bt) do { __builtin_amdgcn_s_setprio(1); _Pragma("unroll") for (int m = 0; m < 4; ++m) _Pragma("unroll") for (int n = 0; n < 2; ++n) _Pragma("unroll") for (int k = 0; k < 2; ++k) \
;         acc[ai][bj][m][n] = __builtin_amdgcn_mfma_f32_16x16x32_bf16(Bt[n][k], At[m][k], acc[ai][bj][m][n], 0, 0, 0); __builtin_amdgcn_s_setprio(0); } while (0)
; #define PG8_WAIT_V(n) asm volatile("s_waitcnt vmcnt(" #n ")" ::: "memory")
; #define PG8_WAIT_L(n) asm volatile("s_waitcnt lgkmcnt(" #n ")" ::: "memory")
; #define PG8_BAR __builtin_amdgcn_s_barrier()
; #define PG8_SCHED __builtin_amdgcn_sched_barrier(0)
; template <class Epi, class Sched, bool ALIGN_EPI = false, bool SP2 = false>
; __device__ __forceinline__ void gemm_phase(PG8_LAS unsigned char* lds, const Gemm g, const Sched& S, const Epi& E) {
;     ...
;             PG8_LDB(B0, 0, 0); PG8_LDB(B1, 0, 1); PG8_SCHED; PG8_LDA(At, 0, 0); PG8_STAGE(PG8_SA(1, 1), a1 + hstepA, voffA);
;             PG8_WAIT_V(8); PG8_WAIT_L(0); PG8_BAR; PG8_MMA(0, 0, At, B0); PG8_MMA(0, 1, At, B1); PG8_BAR; PG8_SCHED;
;             PG8_LDA(At, 0, 1); PG8_STAGE(PG8_SB(0, 0), b2, voffB); PG8_STAGE(PG8_SB(0, 1), b2 + hstep, voffB); PG8_STAGE(PG8_SA(0, 0), a2, voffA);
;             PG8_WAIT_V(8); PG8_WAIT_L(0); PG8_BAR; PG8_MMA(1, 0, At, B0); PG8_MMA(1, 1, At, B1); PG8_BAR; PG8_SCHED;
;             PG8_LDB(B0, 1, 0); PG8_LDB(B1, 1, 1); PG8_SCHED; PG8_LDA(At, 1, 0); PG8_STAGE(PG8_SA(0, 1), a2 + hstepA, voffA);
;             PG8_WAIT_V(8); PG8_WAIT_L(0); PG8_BAR; PG8_MMA(0, 0, At, B0); PG8_MMA(0, 1, At, B1); PG8_BAR; PG8_SCHED;
	s_add_i32 s94, s94, s16
	v_lshl_add_u64 v[150:151], s[12:13], 0, v[156:157]
	s_mov_b32 m0, s94
	ds_read_b128 v[198:201], v186 offset:16384
	ds_read_b128 v[202:205], v186 offset:17408
	ds_read_b128 v[206:209], v186 offset:18432
	ds_read_b128 v[210:213], v186 offset:19456
	ds_read_b128 v[214:217], v186 offset:20480
	ds_read_b128 v[218:221], v186 offset:21504
	ds_read_b128 v[222:225], v186 offset:22528
	ds_read_b128 v[226:229], v186 offset:23552
	global_load_lds_dwordx4 v[150:151], off
	s_add_i32 m0, s94, 0x2000
	s_add_u32 s94, s12, 0x40000
	v_lshl_add_u64 v[166:167], s[12:13], 0, v[160:161]
	s_addc_u32 s95, s13, 0
	s_add_i32 vcc_hi, vcc_hi, s16
	global_load_lds_dwordx4 v[166:167], off
	v_lshl_add_u64 v[230:231], s[94:95], 0, v[156:157]
	s_mov_b32 m0, vcc_hi
	v_lshl_add_u64 v[232:233], s[44:45], 0, v[158:159]
	global_load_lds_dwordx4 v[230:231], off
	v_lshl_add_u64 v[230:231], s[94:95], 0, v[160:161]
	s_add_i32 m0, vcc_hi, 0x2000
	s_nop 0
	global_load_lds_dwordx4 v[230:231], off
	v_lshl_add_u64 v[230:231], s[44:45], 0, v[154:155]
	s_mov_b32 m0, s17
	s_nop 0
	global_load_lds_dwordx4 v[230:231], off
	s_mov_b32 m0, s51
	s_nop 0
	global_load_lds_dwordx4 v[232:233], off
	s_waitcnt vmcnt(8)
	s_waitcnt lgkmcnt(0)
	s_barrier
	s_setprio 1
	s_waitcnt lgkmcnt(0)
	v_mfma_f32_16x16x32_bf16 v[62:65], v[130:133], v[198:201], 0
	v_mfma_f32_16x16x32_bf16 v[58:61], v[138:141], v[198:201], 0
	v_mfma_f32_16x16x32_bf16 v[46:49], v[130:133], v[206:209], 0
	v_mfma_f32_16x16x32_bf16 v[42:45], v[138:141], v[206:209], 0
	v_mfma_f32_16x16x32_bf16 v[30:33], v[130:133], v[214:217], 0
	v_mfma_f32_16x16x32_bf16 v[26:29], v[138:141], v[214:217], 0
	v_mfma_f32_16x16x32_bf16 v[14:17], v[130:133], v[222:225], 0
	v_mfma_f32_16x16x32_bf16 v[10:13], v[138:141], v[222:225], 0
	v_mfma_f32_16x16x32_bf16 v[62:65], v[134:137], v[202:205], v[62:65]
	v_mfma_f32_16x16x32_bf16 v[58:61], v[142:145], v[202:205], v[58:61]
	v_mfma_f32_16x16x32_bf16 v[46:49], v[134:137], v[210:213], v[46:49]
	v_mfma_f32_16x16x32_bf16 v[42:45], v[142:145], v[210:213], v[42:45]
	v_mfma_f32_16x16x32_bf16 v[30:33], v[134:137], v[218:221], v[30:33]
	v_mfma_f32_16x16x32_bf16 v[26:29], v[142:145], v[218:221], v[26:29]
	v_mfma_f32_16x16x32_bf16 v[14:17], v[134:137], v[226:229], v[14:17]
	v_mfma_f32_16x16x32_bf16 v[10:13], v[142:145], v[226:229], v[10:13]
	s_setprio 0
	s_setprio 1
	v_mfma_f32_16x16x32_bf16 v[54:57], v[146:149], v[198:201], 0
	v_mfma_f32_16x16x32_bf16 v[50:53], v[190:193], v[198:201], 0
	v_mfma_f32_16x16x32_bf16 v[38:41], v[146:149], v[206:209], 0
	v_mfma_f32_16x16x32_bf16 v[34:37], v[190:193], v[206:209], 0
	v_mfma_f32_16x16x32_bf16 v[22:25], v[146:149], v[214:217], 0
	v_mfma_f32_16x16x32_bf16 v[18:21], v[190:193], v[214:217], 0
	v_mfma_f32_16x16x32_bf16 v[6:9], v[146:149], v[222:225], 0
	v_mfma_f32_16x16x32_bf16 v[2:5], v[190:193], v[222:225], 0
	v_mfma_f32_16x16x32_bf16 v[54:57], v[170:173], v[202:205], v[54:57]
	v_mfma_f32_16x16x32_bf16 v[50:53], v[194:197], v[202:205], v[50:53]
	v_mfma_f32_16x16x32_bf16 v[38:41], v[170:173], v[210:213], v[38:41]
	v_mfma_f32_16x16x32_bf16 v[34:37], v[194:197], v[210:213], v[34:37]
	v_mfma_f32_16x16x32_bf16 v[22:25], v[170:173], v[218:221], v[22:25]
	v_mfma_f32_16x16x32_bf16 v[18:21], v[194:197], v[218:221], v[18:21]
	v_mfma_f32_16x16x32_bf16 v[6:9], v[170:173], v[226:229], v[6:9]
	v_mfma_f32_16x16x32_bf16 v[2:5], v[194:197], v[226:229], v[2:5]
	s_setprio 0
	s_barrier
	s_add_i32 s94, 0, 0x18000
	v_add_u32_e32 v0, s94, v179
	s_add_i32 s95, 0, 0x1c000
	ds_read_b128 v[130:133], v0
	ds_read_b128 v[134:137], v0 offset:1024
	ds_read_b128 v[138:141], v0 offset:2048
	ds_read_b128 v[142:145], v0 offset:3072
	v_add_u32_e32 v0, s95, v179
	ds_read_b128 v[146:149], v0
	ds_read_b128 v[170:173], v0 offset:1024
	ds_read_b128 v[190:193], v0 offset:2048
	ds_read_b128 v[194:197], v0 offset:3072
	s_add_u32 s44, s44, 0x40000
	s_addc_u32 s45, s45, 0
	s_mov_b32 m0, s35
	v_lshl_add_u64 v[234:235], s[44:45], 0, v[154:155]
	ds_read_b128 v[198:201], v186 offset:32768
	ds_read_b128 v[202:205], v186 offset:33792
	ds_read_b128 v[206:209], v186 offset:34816
	ds_read_b128 v[210:213], v186 offset:35840
	ds_read_b128 v[214:217], v186 offset:36864
	ds_read_b128 v[218:221], v186 offset:37888
	ds_read_b128 v[222:225], v186 offset:38912
	ds_read_b128 v[226:229], v186 offset:39936
	global_load_lds_dwordx4 v[234:235], off
	v_lshl_add_u64 v[234:235], s[44:45], 0, v[158:159]
	s_mov_b32 m0, s30
	s_nop 0
	global_load_lds_dwordx4 v[234:235], off
	s_waitcnt vmcnt(8)
	s_waitcnt lgkmcnt(0)
	s_barrier
; #define PG8_STAGE(bufoff, gbase, voff) do { _Pragma("unroll") for (int _i = 0; _i < 2; ++_i) \
;         __builtin_amdgcn_global_load_lds((const unsigned*)((const char*)(gbase) + (voff)[_i]), (PG8_LAS unsigned*)(lds + (bufoff) + ldsw + _i * 8192), 16, 0, 0); } while (0)
; #define PG8_LDA(dst, b, h) do { _Pragma("unroll") for (int m = 0; m < 4; ++m) _Pragma("unroll") for (int k = 0; k < 2; ++k) dst[m][k] = *(const PG8_LAS bf16x8*)(lds + PG8_SA(b, h) + aoff + m * 2048 + k * 1024); } while (0)
; #define PG8_MMA(ai, bj, At, Bt) do { __builtin_amdgcn_s_setprio(1); _Pragma("unroll") for (int m = 0; m < 4; ++m) _Pragma("unroll") for (int n = 0; n < 2; ++n) _Pragma("unroll") for (int k = 0; k < 2; ++k) \
;         acc[ai][bj][m][n] = __builtin_amdgcn_mfma_f32_16x16x32_bf16(Bt[n][k], At[m][k], acc[ai][bj][m][n], 0, 0, 0); __builtin_amdgcn_s_setprio(0); } while (0)
; #define PG8_WAIT_V(n) asm volatile("s_waitcnt vmcnt(" #n ")" ::: "memory")
; #define PG8_WAIT_L(n) asm volatile("s_waitcnt lgkmcnt(" #n ")" ::: "memory")
; #define PG8_BAR __builtin_amdgcn_s_barrier()
; #define PG8_SCHED __builtin_amdgcn_sched_barrier(0)
; template <class Epi, class Sched, bool ALIGN_EPI = false, bool SP2 = false>
; __device__ __forceinline__ void gemm_phase(PG8_LAS unsigned char* lds, const Gemm g, const Sched& S, const Epi& E) {
;     ...
;             PG8_WAIT_V(8); PG8_WAIT_L(0); PG8_BAR; PG8_MMA(0, 0, At, B0); PG8_MMA(0, 1, At, B1); PG8_BAR; PG8_SCHED;
;             PG8_LDA(At, 1, 1); PG8_STAGE(PG8_SB(1, 0), b3, voffB); PG8_STAGE(PG8_SB(1, 1), b3 + hstep, voffB); PG8_STAGE(PG8_SA(1, 0), a3, voffA);
;             PG8_WAIT_V(8); PG8_WAIT_L(0); PG8_BAR; PG8_MMA(1, 0, At, B0); PG8_MMA(1, 1, At, B1); PG8_BAR; PG8_SCHED;
	s_setprio 1
	s_waitcnt lgkmcnt(0)
	v_mfma_f32_16x16x32_bf16 v[126:129], v[130:133], v[198:201], v[126:129]
	v_mfma_f32_16x16x32_bf16 v[122:125], v[138:141], v[198:201], v[122:125]
	v_mfma_f32_16x16x32_bf16 v[110:113], v[130:133], v[206:209], v[110:113]
	v_mfma_f32_16x16x32_bf16 v[106:109], v[138:141], v[206:209], v[106:109]
	v_mfma_f32_16x16x32_bf16 v[94:97], v[130:133], v[214:217], v[94:97]
	v_mfma_f32_16x16x32_bf16 v[90:93], v[138:141], v[214:217], v[90:93]
	v_mfma_f32_16x16x32_bf16 v[78:81], v[130:133], v[222:225], v[78:81]
	v_mfma_f32_16x16x32_bf16 v[74:77], v[138:141], v[222:225], v[74:77]
	v_mfma_f32_16x16x32_bf16 v[126:129], v[134:137], v[202:205], v[126:129]
	v_mfma_f32_16x16x32_bf16 v[122:125], v[142:145], v[202:205], v[122:125]
	v_mfma_f32_16x16x32_bf16 v[110:113], v[134:137], v[210:213], v[110:113]
	v_mfma_f32_16x16x32_bf16 v[106:109], v[142:145], v[210:213], v[106:109]
	v_mfma_f32_16x16x32_bf16 v[94:97], v[134:137], v[218:221], v[94:97]
	v_mfma_f32_16x16x32_bf16 v[90:93], v[142:145], v[218:221], v[90:93]
	v_mfma_f32_16x16x32_bf16 v[78:81], v[134:137], v[226:229], v[78:81]
	v_mfma_f32_16x16x32_bf16 v[74:77], v[142:145], v[226:229], v[74:77]
	s_setprio 0
	s_setprio 1
	v_mfma_f32_16x16x32_bf16 v[118:121], v[146:149], v[198:201], v[118:121]
	v_mfma_f32_16x16x32_bf16 v[114:117], v[190:193], v[198:201], v[114:117]
	v_mfma_f32_16x16x32_bf16 v[102:105], v[146:149], v[206:209], v[102:105]
	v_mfma_f32_16x16x32_bf16 v[98:101], v[190:193], v[206:209], v[98:101]
	v_mfma_f32_16x16x32_bf16 v[86:89], v[146:149], v[214:217], v[86:89]
	v_mfma_f32_16x16x32_bf16 v[82:85], v[190:193], v[214:217], v[82:85]
	v_mfma_f32_16x16x32_bf16 v[70:73], v[146:149], v[222:225], v[70:73]
	v_mfma_f32_16x16x32_bf16 v[66:69], v[190:193], v[222:225], v[66:69]
	v_mfma_f32_16x16x32_bf16 v[118:121], v[170:173], v[202:205], v[118:121]
	v_mfma_f32_16x16x32_bf16 v[114:117], v[194:197], v[202:205], v[114:117]
	v_mfma_f32_16x16x32_bf16 v[102:105], v[170:173], v[210:213], v[102:105]
	v_mfma_f32_16x16x32_bf16 v[98:101], v[194:197], v[210:213], v[98:101]
	v_mfma_f32_16x16x32_bf16 v[86:89], v[170:173], v[218:221], v[86:89]
	v_mfma_f32_16x16x32_bf16 v[82:85], v[194:197], v[218:221], v[82:85]
	v_mfma_f32_16x16x32_bf16 v[70:73], v[170:173], v[226:229], v[70:73]
	v_mfma_f32_16x16x32_bf16 v[66:69], v[194:197], v[226:229], v[66:69]
	s_setprio 0
	s_barrier
	s_add_i32 s44, s94, s16
	v_lshl_add_u64 v[150:151], v[150:151], 0, s[48:49]
	s_mov_b32 m0, s44
	ds_read_b128 v[198:201], v186 offset:49152
	ds_read_b128 v[202:205], v186 offset:50176
	ds_read_b128 v[206:209], v186 offset:51200
	ds_read_b128 v[210:213], v186 offset:52224
	ds_read_b128 v[214:217], v186 offset:53248
	ds_read_b128 v[218:221], v186 offset:54272
	ds_read_b128 v[222:225], v186 offset:55296
	ds_read_b128 v[226:229], v186 offset:56320
	global_load_lds_dwordx4 v[150:151], off
	s_add_i32 m0, s44, 0x2000
	s_add_u32 s12, s12, 0x40080
	v_lshl_add_u64 v[150:151], v[166:167], 0, s[48:49]
	s_addc_u32 s13, s13, 0
	s_add_i32 s44, s95, s16
	global_load_lds_dwordx4 v[150:151], off
	v_lshl_add_u64 v[150:151], s[12:13], 0, v[156:157]
	s_mov_b32 m0, s44
	s_nop 0
	global_load_lds_dwordx4 v[150:151], off
	v_lshl_add_u64 v[150:151], s[12:13], 0, v[160:161]
	s_add_i32 m0, s44, 0x2000
	s_nop 0
	global_load_lds_dwordx4 v[150:151], off
	v_lshl_add_u64 v[150:151], v[230:231], 0, s[48:49]
	s_mov_b32 m0, s59
	s_nop 0
	global_load_lds_dwordx4 v[150:151], off
	v_lshl_add_u64 v[150:151], v[232:233], 0, s[48:49]
	s_mov_b32 m0, s86
	s_nop 0
	global_load_lds_dwordx4 v[150:151], off
	s_waitcnt vmcnt(8)
	s_waitcnt lgkmcnt(0)
	s_barrier
	s_setprio 1
	s_waitcnt lgkmcnt(0)
	v_mfma_f32_16x16x32_bf16 v[62:65], v[130:133], v[198:201], v[62:65]
	v_mfma_f32_16x16x32_bf16 v[58:61], v[138:141], v[198:201], v[58:61]
	v_mfma_f32_16x16x32_bf16 v[46:49], v[130:133], v[206:209], v[46:49]
	v_mfma_f32_16x16x32_bf16 v[42:45], v[138:141], v[206:209], v[42:45]
	v_mfma_f32_16x16x32_bf16 v[30:33], v[130:133], v[214:217], v[30:33]
	v_mfma_f32_16x16x32_bf16 v[26:29], v[138:141], v[214:217], v[26:29]
	v_mfma_f32_16x16x32_bf16 v[14:17], v[130:133], v[222:225], v[14:17]
	v_mfma_f32_16x16x32_bf16 v[10:13], v[138:141], v[222:225], v[10:13]
	v_mfma_f32_16x16x32_bf16 v[62:65], v[134:137], v[202:205], v[62:65]
	v_mfma_f32_16x16x32_bf16 v[58:61], v[142:145], v[202:205], v[58:61]
	v_mfma_f32_16x16x32_bf16 v[46:49], v[134:137], v[210:213], v[46:49]
	v_mfma_f32_16x16x32_bf16 v[42:45], v[142:145], v[210:213], v[42:45]
	v_mfma_f32_16x16x32_bf16 v[30:33], v[134:137], v[218:221], v[30:33]
	v_mfma_f32_16x16x32_bf16 v[26:29], v[142:145], v[218:221], v[26:29]
	v_mfma_f32_16x16x32_bf16 v[14:17], v[134:137], v[226:229], v[14:17]
	v_mfma_f32_16x16x32_bf16 v[10:13], v[142:145], v[226:229], v[10:13]
	s_setprio 0
	s_setprio 1
	v_mfma_f32_16x16x32_bf16 v[54:57], v[146:149], v[198:201], v[54:57]
	v_mfma_f32_16x16x32_bf16 v[50:53], v[190:193], v[198:201], v[50:53]
	v_mfma_f32_16x16x32_bf16 v[38:41], v[146:149], v[206:209], v[38:41]
	v_mfma_f32_16x16x32_bf16 v[34:37], v[190:193], v[206:209], v[34:37]
	v_mfma_f32_16x16x32_bf16 v[22:25], v[146:149], v[214:217], v[22:25]
	v_mfma_f32_16x16x32_bf16 v[18:21], v[190:193], v[214:217], v[18:21]
	v_mfma_f32_16x16x32_bf16 v[6:9], v[146:149], v[222:225], v[6:9]
	v_mfma_f32_16x16x32_bf16 v[2:5], v[190:193], v[222:225], v[2:5]
	v_mfma_f32_16x16x32_bf16 v[54:57], v[170:173], v[202:205], v[54:57]
	v_mfma_f32_16x16x32_bf16 v[50:53], v[194:197], v[202:205], v[50:53]
	v_mfma_f32_16x16x32_bf16 v[38:41], v[170:173], v[210:213], v[38:41]
	v_mfma_f32_16x16x32_bf16 v[34:37], v[194:197], v[210:213], v[34:37]
	v_mfma_f32_16x16x32_bf16 v[22:25], v[170:173], v[218:221], v[22:25]
	v_mfma_f32_16x16x32_bf16 v[18:21], v[194:197], v[218:221], v[18:21]
	v_mfma_f32_16x16x32_bf16 v[6:9], v[170:173], v[226:229], v[6:9]
	v_mfma_f32_16x16x32_bf16 v[2:5], v[194:197], v[226:229], v[2:5]
	s_setprio 0
	s_barrier
	s_add_i32 vcc_lo, vcc_lo, 2
	s_add_u32 s10, s10, 0x100
	s_addc_u32 s11, s11, 0
	s_add_u32 s47, s47, 0x100
	s_addc_u32 s63, s63, 0

;     __device__ __forceinline__ void operator()(const f32x4 (&acc)[2][2][4][2], const Unit& u, int wr, int wc, int fr, int fq, int) const {
;     ...
;             const f32x4 w0 = *(const f32x4*)(convw + c0), w1 = *(const f32x4*)(convw + 1024 + c0), w2 = *(const f32x4*)(convw + 2048 + c0), ga = *(const f32x4*)(gconv + c0);
;             float rsv[2][4];
; #pragma unroll
;             for (int ai = 0; ai < 2; ++ai)
; #pragma unroll
;                 for (int m = 0; m < 4; ++m) rsv[ai][m] = __builtin_amdgcn_rsqf(rowss[row0 + ai * HALF + m * 16] * (1.0f / 1024.0f) + RMS_EPS);
.LBB0_334:
	s_andn2_b64 vcc, exec, s[10:11]
	s_cbranch_vccnz .LBB0_365
	v_ashrrev_i32_e32 v135, 31, v134
	v_lshlrev_b32_e32 v194, 2, v178
	v_add_u32_e32 v194, 0x21000, v194
	v_lshlrev_b32_e32 v195, 2, v182
	v_add_u32_e32 v195, 0x21400, v195
	ds_read_b32 v0, v194
	ds_read_b32 v191, v194 offset:64
	ds_read_b32 v190, v194 offset:128
	ds_read_b32 v62, v194 offset:192
	ds_read_b32 v189, v194 offset:512
	ds_read_b32 v111, v194 offset:576
	ds_read_b32 v95, v194 offset:640
	ds_read_b32 v63, v194 offset:704
	ds_read_b128 v[134:137], v195
	ds_read_b128 v[138:141], v195 offset:256
	ds_read_b128 v[142:145], v195 offset:512
	ds_read_b128 v[130:133], v195 offset:768
	s_waitcnt lgkmcnt(0)
	v_fmamk_f32 v14, v62, 0x3a800000, v169
	v_rsq_f32_e32 v94, v14
	v_fmamk_f32 v15, v63, 0x3a800000, v169
	v_rsq_f32_e32 v30, v15
	v_mul_f32_e32 v110, v94, v94
	v_mul_f32_e32 v46, v30, v30
	s_and_saveexec_b64 s[10:11], s[4:5]
	s_cbranch_execz .LBB0_337
	v_pk_mul_f32 v[14:15], v[80:81], v[76:77]
	v_pk_mul_f32 v[146:147], v[74:75], v[110:111] op_sel_hi:[1,0]
	v_pk_mul_f32 v[148:149], v[14:15], v[110:111] op_sel_hi:[1,0]
	v_pk_mul_f32 v[14:15], v[16:17], v[12:13]
	ds_write_b128 v187, v[146:149]
	v_pk_mul_f32 v[146:147], v[10:11], v[46:47] op_sel_hi:[1,0]
	v_pk_mul_f32 v[148:149], v[14:15], v[46:47] op_sel_hi:[1,0]
	ds_write_b128 v188, v[146:149]

; __device__ __forceinline__ unsigned cvt_pk_bf16(float lo, float hi) { unsigned r; asm volatile("v_cvt_pk_bf16_f32 %0, %1, %2" : "=v"(r) : "v"(lo), "v"(hi)); return r; }
;     __device__ __forceinline__ void operator()(const f32x4 (&acc)[2][2][4][2], const Unit& u, int wr, int wc, int fr, int fq, int) const {
;     ...
;             for (int m = 0; m < 4; ++m) { const int r = row0 + ai * HALF + m * 16; const float sc = __builtin_amdgcn_rsqf(ssq[r] * (1.0f / 1024.0f) + RMS_EPS);
; #pragma unroll
;                 for (int bj = 0; bj < 2; ++bj) { const f32x4 v0 = acc[ai][bj][m][0] * sc, v1 = acc[ai][bj][m][1] * sc;
;                     u32x4 w; w.x = cvt_pk_bf16(v0[0], v0[1]); w.y = cvt_pk_bf16(v0[2], v0[3]); w.z = cvt_pk_bf16(v1[0], v1[1]); w.w = cvt_pk_bf16(v1[2], v1[3]);
;                     *(u32x4*)((char*)part + (unsigned)((r * 1024 + col0 + bj * HALF) * 2)) = w; }
;                 asm volatile("" ::: "memory"); }
.LBB0_419:
	v_readlane_b32 s4, v255, 22
	s_add_u32 s4, s54, s4
	s_addc_u32 s5, s55, 0
	s_add_u32 s4, s4, 0x3c600000
	v_readlane_b32 s6, v255, 0
	s_addc_u32 s5, s5, 0
	v_readlane_b32 s7, v255, 1
	s_and_b64 s[6:7], s[6:7], exec
	s_cselect_b32 s6, s8, s10
	v_readlane_b32 s8, v255, 5
	s_cselect_b32 s7, s9, s11
	s_add_u32 s6, s6, 0x40000
	v_add_u32_e32 v132, s8, v132
	s_addc_u32 s7, s7, 0
	v_ashrrev_i32_e32 v133, 31, v132
	v_lshl_add_u64 v[130:131], v[132:133], 2, s[6:7]
	global_load_dword v0, v[130:131], off
	global_load_dword v191, v[130:131], off offset:64
	global_load_dword v192, v[130:131], off offset:128
	global_load_dword v193, v[130:131], off offset:192
	global_load_dword v194, v[130:131], off offset:512
	global_load_dword v195, v[130:131], off offset:576
	global_load_dword v196, v[130:131], off offset:640
	global_load_dword v197, v[130:131], off offset:704
	s_lshl_b32 s0, s0, 6
	v_readlane_b32 s8, v255, 2
	s_or_b32 s0, s0, s8
	v_or_b32_e32 v133, s0, v134
	v_or_b32_e32 v74, 16, v132
	v_ashrrev_i32_e32 v75, 31, v74
	v_lshl_add_u64 v[76:77], v[74:75], 2, s[6:7]
	v_mov_b32_e32 v236, v176
	v_mov_b64_e32 v[238:239], 0x400
	s_waitcnt vmcnt(7)
	v_fmamk_f32 v0, v0, 0x3a800000, v169
	v_rsq_f32_e32 v70, v0
	v_lshl_or_b32 v0, v132, 11, v133
	v_pk_mul_f32 v[72:73], v[116:117], v[70:71] op_sel_hi:[1,0]
	v_pk_mul_f32 v[78:79], v[114:115], v[70:71] op_sel_hi:[1,0]
	v_pk_mul_f32 v[80:81], v[120:121], v[70:71] op_sel_hi:[1,0]
	v_pk_mul_f32 v[114:115], v[118:119], v[70:71] op_sel_hi:[1,0]
	v_pk_mul_f32 v[116:117], v[124:125], v[70:71] op_sel_hi:[1,0]
	v_pk_mul_f32 v[118:119], v[122:123], v[70:71] op_sel_hi:[1,0]
	v_pk_mul_f32 v[120:121], v[128:129], v[70:71] op_sel_hi:[1,0]
	v_pk_mul_f32 v[122:123], v[126:127], v[70:71] op_sel_hi:[1,0]
	v_cvt_pk_bf16_f32 v70, v78, v79
	v_cvt_pk_bf16_f32 v71, v72, v73
	v_cvt_pk_bf16_f32 v72, v114, v115
	v_cvt_pk_bf16_f32 v73, v80, v81
	global_store_dwordx4 v0, v[70:73], s[4:5]
	s_nop 1
	v_cvt_pk_bf16_f32 v70, v118, v119
	v_cvt_pk_bf16_f32 v71, v116, v117
	v_cvt_pk_bf16_f32 v72, v122, v123
	v_cvt_pk_bf16_f32 v73, v120, v121
	global_store_dwordx4 v0, v[70:73], s[4:5] offset:256
	s_nop 0
	v_or_b32_e32 v76, 32, v132
	v_ashrrev_i32_e32 v77, 31, v76
	v_lshl_add_u64 v[78:79], v[76:77], 2, s[6:7]
	v_lshl_or_b32 v77, v74, 11, v133
	s_waitcnt vmcnt(7)
	v_mov_b32_e32 v70, v191
	v_fmamk_f32 v70, v70, 0x3a800000, v169
	v_rsq_f32_e32 v70, v70
	s_nop 0
	v_pk_mul_f32 v[72:73], v[100:101], v[70:71] op_sel_hi:[1,0]
	v_pk_mul_f32 v[74:75], v[98:99], v[70:71] op_sel_hi:[1,0]
	v_pk_mul_f32 v[80:81], v[104:105], v[70:71] op_sel_hi:[1,0]
	v_pk_mul_f32 v[98:99], v[102:103], v[70:71] op_sel_hi:[1,0]
	v_pk_mul_f32 v[100:101], v[108:109], v[70:71] op_sel_hi:[1,0]
	v_pk_mul_f32 v[102:103], v[106:107], v[70:71] op_sel_hi:[1,0]
	v_pk_mul_f32 v[104:105], v[112:113], v[70:71] op_sel_hi:[1,0]
	v_pk_mul_f32 v[106:107], v[110:111], v[70:71] op_sel_hi:[1,0]
	v_cvt_pk_bf16_f32 v70, v74, v75
	v_cvt_pk_bf16_f32 v71, v72, v73
	v_cvt_pk_bf16_f32 v72, v98, v99
	v_cvt_pk_bf16_f32 v73, v80, v81
	global_store_dwordx4 v77, v[70:73], s[4:5]
	v_or_b32_e32 v74, 48, v132
	v_ashrrev_i32_e32 v75, 31, v74
	v_cvt_pk_bf16_f32 v70, v102, v103
	v_cvt_pk_bf16_f32 v71, v100, v101
	v_cvt_pk_bf16_f32 v72, v106, v107
	v_cvt_pk_bf16_f32 v73, v104, v105
	global_store_dwordx4 v77, v[70:73], s[4:5] offset:256
	s_nop 0
	v_lshl_add_u64 v[78:79], v[74:75], 2, s[6:7]
	v_lshl_or_b32 v75, v76, 11, v133
	s_waitcnt vmcnt(7)
	v_mov_b32_e32 v70, v192
	v_fmamk_f32 v70, v70, 0x3a800000, v169
	v_rsq_f32_e32 v70, v70
	s_nop 0
	v_pk_mul_f32 v[72:73], v[84:85], v[70:71] op_sel_hi:[1,0]
	v_pk_mul_f32 v[76:77], v[82:83], v[70:71] op_sel_hi:[1,0]
	v_pk_mul_f32 v[80:81], v[88:89], v[70:71] op_sel_hi:[1,0]
	v_pk_mul_f32 v[82:83], v[86:87], v[70:71] op_sel_hi:[1,0]
	v_pk_mul_f32 v[84:85], v[92:93], v[70:71] op_sel_hi:[1,0]
	v_pk_mul_f32 v[86:87], v[90:91], v[70:71] op_sel_hi:[1,0]
	v_pk_mul_f32 v[88:89], v[96:97], v[70:71] op_sel_hi:[1,0]
	v_pk_mul_f32 v[90:91], v[94:95], v[70:71] op_sel_hi:[1,0]
	v_cvt_pk_bf16_f32 v70, v76, v77
	v_cvt_pk_bf16_f32 v71, v72, v73
	v_cvt_pk_bf16_f32 v72, v82, v83
	v_cvt_pk_bf16_f32 v73, v80, v81
	global_store_dwordx4 v75, v[70:73], s[4:5]
	s_nop 1
	v_cvt_pk_bf16_f32 v70, v86, v87
	v_cvt_pk_bf16_f32 v71, v84, v85
	v_cvt_pk_bf16_f32 v72, v90, v91
	v_cvt_pk_bf16_f32 v73, v88, v89
	global_store_dwordx4 v75, v[70:73], s[4:5] offset:256
	s_nop 0
	v_lshl_or_b32 v86, v74, 11, v133
	s_waitcnt vmcnt(7)
; __device__ __forceinline__ unsigned cvt_pk_bf16(float lo, float hi) { unsigned r; asm volatile("v_cvt_pk_bf16_f32 %0, %1, %2" : "=v"(r) : "v"(lo), "v"(hi)); return r; }
;     __device__ __forceinline__ void operator()(const f32x4 (&acc)[2][2][4][2], const Unit& u, int wr, int wc, int fr, int fq, int) const {
;     ...
;             for (int m = 0; m < 4; ++m) { const int r = row0 + ai * HALF + m * 16; const float sc = __builtin_amdgcn_rsqf(ssq[r] * (1.0f / 1024.0f) + RMS_EPS);
; #pragma unroll
;                 for (int bj = 0; bj < 2; ++bj) { const f32x4 v0 = acc[ai][bj][m][0] * sc, v1 = acc[ai][bj][m][1] * sc;
;                     u32x4 w; w.x = cvt_pk_bf16(v0[0], v0[1]); w.y = cvt_pk_bf16(v0[2], v0[3]); w.z = cvt_pk_bf16(v1[0], v1[1]); w.w = cvt_pk_bf16(v1[2], v1[3]);
;                     *(u32x4*)((char*)part + (unsigned)((r * 1024 + col0 + bj * HALF) * 2)) = w; }
;                 asm volatile("" ::: "memory"); }
	v_mov_b32_e32 v70, v193
	v_fmamk_f32 v70, v70, 0x3a800000, v169
	v_rsq_f32_e32 v70, v70
	s_nop 0
	v_pk_mul_f32 v[72:73], v[172:173], v[70:71] op_sel_hi:[1,0]
	v_pk_mul_f32 v[74:75], v[170:171], v[70:71] op_sel_hi:[1,0]
	v_pk_mul_f32 v[76:77], v[150:151], v[70:71] op_sel_hi:[1,0]
	v_pk_mul_f32 v[78:79], v[148:149], v[70:71] op_sel_hi:[1,0]
	v_pk_mul_f32 v[80:81], v[138:139], v[70:71] op_sel_hi:[1,0]
	v_pk_mul_f32 v[82:83], v[136:137], v[70:71] op_sel_hi:[1,0]
	v_pk_mul_f32 v[84:85], v[68:69], v[70:71] op_sel_hi:[1,0]
	v_pk_mul_f32 v[70:71], v[66:67], v[70:71] op_sel_hi:[1,0]
	v_cvt_pk_bf16_f32 v66, v74, v75
	v_cvt_pk_bf16_f32 v67, v72, v73
	v_cvt_pk_bf16_f32 v68, v78, v79
	v_cvt_pk_bf16_f32 v69, v76, v77
	global_store_dwordx4 v86, v[66:69], s[4:5]
	s_nop 1
	v_cvt_pk_bf16_f32 v66, v82, v83
	v_cvt_pk_bf16_f32 v67, v80, v81
	v_cvt_pk_bf16_f32 v68, v70, v71
	v_cvt_pk_bf16_f32 v69, v84, v85
	global_store_dwordx4 v86, v[66:69], s[4:5] offset:256
	s_nop 0
	v_add_u32_e32 v70, 0x40000, v0
	s_waitcnt vmcnt(7)
	v_mov_b32_e32 v66, v194
	v_fmamk_f32 v66, v66, 0x3a800000, v169
	v_rsq_f32_e32 v66, v66
	s_nop 0
	v_pk_mul_f32 v[64:65], v[64:65], v[66:67] op_sel_hi:[1,0]
	v_pk_mul_f32 v[62:63], v[62:63], v[66:67] op_sel_hi:[1,0]
	v_pk_mul_f32 v[60:61], v[60:61], v[66:67] op_sel_hi:[1,0]
	v_pk_mul_f32 v[58:59], v[58:59], v[66:67] op_sel_hi:[1,0]
	v_pk_mul_f32 v[56:57], v[56:57], v[66:67] op_sel_hi:[1,0]
	v_pk_mul_f32 v[54:55], v[54:55], v[66:67] op_sel_hi:[1,0]
	v_pk_mul_f32 v[68:69], v[52:53], v[66:67] op_sel_hi:[1,0]
	v_pk_mul_f32 v[66:67], v[50:51], v[66:67] op_sel_hi:[1,0]
	v_cvt_pk_bf16_f32 v50, v62, v63
	v_cvt_pk_bf16_f32 v51, v64, v65
	v_cvt_pk_bf16_f32 v52, v58, v59
	v_cvt_pk_bf16_f32 v53, v60, v61
	global_store_dwordx4 v70, v[50:53], s[4:5]
	s_nop 1
	v_cvt_pk_bf16_f32 v50, v54, v55
	v_cvt_pk_bf16_f32 v51, v56, v57
	v_cvt_pk_bf16_f32 v52, v66, v67
	v_cvt_pk_bf16_f32 v53, v68, v69
	global_store_dwordx4 v70, v[50:53], s[4:5] offset:256
	s_nop 0
	v_add_u32_e32 v54, 0x48000, v0
	s_waitcnt vmcnt(7)
	v_mov_b32_e32 v50, v195
	v_fmamk_f32 v50, v50, 0x3a800000, v169
	v_rsq_f32_e32 v50, v50
	s_nop 0
	v_pk_mul_f32 v[48:49], v[48:49], v[50:51] op_sel_hi:[1,0]
	v_pk_mul_f32 v[46:47], v[46:47], v[50:51] op_sel_hi:[1,0]
	v_pk_mul_f32 v[44:45], v[44:45], v[50:51] op_sel_hi:[1,0]
	v_pk_mul_f32 v[42:43], v[42:43], v[50:51] op_sel_hi:[1,0]
	v_pk_mul_f32 v[40:41], v[40:41], v[50:51] op_sel_hi:[1,0]
	v_pk_mul_f32 v[38:39], v[38:39], v[50:51] op_sel_hi:[1,0]
	v_pk_mul_f32 v[52:53], v[36:37], v[50:51] op_sel_hi:[1,0]
	v_pk_mul_f32 v[50:51], v[34:35], v[50:51] op_sel_hi:[1,0]
	v_cvt_pk_bf16_f32 v34, v46, v47
	v_cvt_pk_bf16_f32 v35, v48, v49
	v_cvt_pk_bf16_f32 v36, v42, v43
	v_cvt_pk_bf16_f32 v37, v44, v45
	global_store_dwordx4 v54, v[34:37], s[4:5]
	s_nop 1
	v_cvt_pk_bf16_f32 v34, v38, v39
	v_cvt_pk_bf16_f32 v35, v40, v41
	v_cvt_pk_bf16_f32 v36, v50, v51
	v_cvt_pk_bf16_f32 v37, v52, v53
	global_store_dwordx4 v54, v[34:37], s[4:5] offset:256
	s_nop 0
	v_add_u32_e32 v38, 0x50000, v0
	v_add_u32_e32 v0, 0x58000, v0
	s_waitcnt vmcnt(7)
	v_mov_b32_e32 v34, v196
	v_fmamk_f32 v34, v34, 0x3a800000, v169
	v_rsq_f32_e32 v34, v34
	s_nop 0
	v_pk_mul_f32 v[32:33], v[32:33], v[34:35] op_sel_hi:[1,0]
	v_pk_mul_f32 v[30:31], v[30:31], v[34:35] op_sel_hi:[1,0]
	v_pk_mul_f32 v[28:29], v[28:29], v[34:35] op_sel_hi:[1,0]
	v_pk_mul_f32 v[26:27], v[26:27], v[34:35] op_sel_hi:[1,0]
	v_pk_mul_f32 v[24:25], v[24:25], v[34:35] op_sel_hi:[1,0]
	v_pk_mul_f32 v[22:23], v[22:23], v[34:35] op_sel_hi:[1,0]
	v_pk_mul_f32 v[36:37], v[20:21], v[34:35] op_sel_hi:[1,0]
	v_pk_mul_f32 v[34:35], v[18:19], v[34:35] op_sel_hi:[1,0]
	v_cvt_pk_bf16_f32 v18, v30, v31
	v_cvt_pk_bf16_f32 v19, v32, v33
	v_cvt_pk_bf16_f32 v20, v26, v27
	v_cvt_pk_bf16_f32 v21, v28, v29
	global_store_dwordx4 v38, v[18:21], s[4:5]
	s_nop 1
	v_cvt_pk_bf16_f32 v18, v22, v23
	v_cvt_pk_bf16_f32 v19, v24, v25
	v_cvt_pk_bf16_f32 v20, v34, v35
	v_cvt_pk_bf16_f32 v21, v36, v37
	global_store_dwordx4 v38, v[18:21], s[4:5] offset:256
	s_nop 0
	s_waitcnt vmcnt(7)
	v_mov_b32_e32 v18, v197
	v_fmamk_f32 v18, v18, 0x3a800000, v169
	v_rsq_f32_e32 v18, v18
	s_nop 0
	v_pk_mul_f32 v[16:17], v[16:17], v[18:19] op_sel_hi:[1,0]
	v_pk_mul_f32 v[14:15], v[14:15], v[18:19] op_sel_hi:[1,0]
	v_pk_mul_f32 v[12:13], v[12:13], v[18:19] op_sel_hi:[1,0]
	v_pk_mul_f32 v[10:11], v[10:11], v[18:19] op_sel_hi:[1,0]
	v_pk_mul_f32 v[8:9], v[8:9], v[18:19] op_sel_hi:[1,0]
	v_pk_mul_f32 v[6:7], v[6:7], v[18:19] op_sel_hi:[1,0]
	v_pk_mul_f32 v[20:21], v[4:5], v[18:19] op_sel_hi:[1,0]
	v_pk_mul_f32 v[18:19], v[2:3], v[18:19] op_sel_hi:[1,0]
	v_cvt_pk_bf16_f32 v2, v14, v15
	v_cvt_pk_bf16_f32 v3, v16, v17
	v_cvt_pk_bf16_f32 v4, v10, v11
	v_cvt_pk_bf16_f32 v5, v12, v13
	global_store_dwordx4 v0, v[2:5], s[4:5]
	s_nop 1
	v_cvt_pk_bf16_f32 v2, v6, v7
	v_cvt_pk_bf16_f32 v3, v8, v9
	v_cvt_pk_bf16_f32 v4, v18, v19
	v_cvt_pk_bf16_f32 v5, v20, v21
	global_store_dwordx4 v0, v[2:5], s[4:5] offset:256
	s_waitcnt vmcnt(0)
	s_barrier
